# c11 + GEMM phase prologue issues the K-tile-1 stages before the first wait (vmcnt 10)
# speedup vs baseline: 1.0010x; 1.0010x over previous
; #define PG8_STAGE(bufoff, gbase, voff) do { _Pragma("unroll") for (int _i = 0; _i < 2; ++_i) \
;         __builtin_amdgcn_global_load_lds((const unsigned*)((const char*)(gbase) + (voff)[_i]), (PG8_LAS unsigned*)(lds + (bufoff) + ldsw + _i * 8192), 16, 0, 0); } while (0)
; #define PG8_WAIT_V(n) asm volatile("s_waitcnt vmcnt(" #n ")" ::: "memory")
; #define PG8_BAR __builtin_amdgcn_s_barrier()
; template <class Epi, class Sched>
; __device__ __forceinline__ void gemm_phase(PG8_LAS unsigned char* lds, const Gemm g, const Sched& S, const Epi& E, int wv) {
;     ...
;     PG8_STAGE(PG8_SB(0, 0), cB, voffB); PG8_STAGE(PG8_SA(0, 0), cA, voffA); PG8_STAGE(PG8_SB(0, 1), cB + hstep, voffB); PG8_STAGE(PG8_SA(0, 1), cA + hstepA, voffA);
;     if (wr == 1) PG8_BAR;
;     PG8_WAIT_V(4); PG8_BAR;
;     PG8_STAGE(PG8_SB(1, 0), cB + kstep, voffB); PG8_STAGE(PG8_SA(1, 0), cA + kstep, voffA); PG8_STAGE(PG8_SB(1, 1), cB + hstep + kstep, voffB);
;     PG8_WAIT_V(6); PG8_BAR;
.LBB0_34:
	v_bfe_u32 v16, v0, 4, 2
	v_and_b32_e32 v188, 15, v0
	v_lshlrev_b32_e32 v17, 4, v16
	v_lshlrev_b32_e32 v18, 2, v0
	s_sext_i32_i8 s88, s4
	v_lshl_or_b32 v17, v188, 6, v17
	s_lshl_b32 s4, s6, 13
	v_and_b32_e32 v18, 32, v18
	v_bitop3_b32 v19, v17, s4, v18 bitop3:0xde
	s_lshl_b32 s4, s5, 5
	s_lshl_b32 s77, s6, 6
	s_and_b32 s6, s4, 0x60
	s_add_i32 m0, s59, 0x18000
	v_lshl_add_u64 v[8:9], v[8:9], 0, s[48:49]
	s_lshl_b32 s4, s6, 7
	global_load_lds_dwordx4 v[8:9], off
	v_lshl_add_u64 v[6:7], v[6:7], 0, s[48:49]
	s_add_i32 m0, s59, 0x1a000
	s_add_i32 s79, s59, 0x8000
	s_add_i32 s86, s59, 0xa000
	v_bitop3_b32 v189, v17, s4, v18 bitop3:0xde
	global_load_lds_dwordx4 v[6:7], off
	v_lshl_add_u64 v[4:5], v[4:5], 0, s[48:49]
	s_mov_b32 m0, s79
	s_add_u32 s4, s80, 0x40080
	global_load_lds_dwordx4 v[4:5], off
	v_lshl_add_u64 v[2:3], v[2:3], 0, s[48:49]
	s_mov_b32 m0, s86
	s_addc_u32 s5, s81, 0
	global_load_lds_dwordx4 v[2:3], off
	s_add_i32 m0, s59, 0x1c000
	v_lshl_add_u64 v[2:3], s[4:5], 0, v[180:181]
	global_load_lds_dwordx4 v[2:3], off
	v_lshl_add_u64 v[2:3], s[4:5], 0, v[178:179]
	s_add_i32 m0, s59, 0x1e000
	v_and_b32_e32 v190, 7, v0
	global_load_lds_dwordx4 v[2:3], off
	s_waitcnt vmcnt(10)
	s_barrier
	v_lshlrev_b32_e32 v0, 14, v10
	v_and_b32_e32 v0, 0xffff8000, v0
	v_lshl_add_u32 v0, v11, 11, v0
	v_and_b32_e32 v2, 1, v10
	v_lshl_or_b32 v0, v2, 6, v0
	v_lshl_add_u32 v182, v12, 1, v0
	v_lshlrev_b32_e32 v0, 14, v13
	v_and_b32_e32 v0, 0xffff8000, v0
	s_waitcnt vmcnt(6)
	v_lshl_add_u32 v0, v14, 11, v0
	v_and_b32_e32 v2, 1, v13
	v_cmp_gt_u32_e64 s[4:5], 8, v188
	v_lshl_or_b32 v0, v2, 6, v0
	s_mov_b32 s87, 0
	v_cndmask_b32_e64 v191, 64, 0, s[4:5]
	v_lshl_or_b32 v192, v16, 2, s6
	v_mov_b32_e32 v183, v1
	v_lshl_add_u32 v184, v15, 1, v0
	v_mov_b32_e32 v185, v1
	v_add_u32_e32 v193, 0, v19
	s_barrier

; #define PG8_STAGE(bufoff, gbase, voff) do { _Pragma("unroll") for (int _i = 0; _i < 2; ++_i) \
;         __builtin_amdgcn_global_load_lds((const unsigned*)((const char*)(gbase) + (voff)[_i]), (PG8_LAS unsigned*)(lds + (bufoff) + ldsw + _i * 8192), 16, 0, 0); } while (0)
; #define PG8_WAIT_V(n) asm volatile("s_waitcnt vmcnt(" #n ")" ::: "memory")
; #define PG8_BAR __builtin_amdgcn_s_barrier()
; template <class Epi, class Sched>
; __device__ __forceinline__ void gemm_phase(PG8_LAS unsigned char* lds, const Gemm g, const Sched& S, const Epi& E, int wv) {
;     ...
;     for (int i = 0; i < 2; ++i) { int R, C; stage_rc(tid * 16 + i * 8192, R, C); const int Rb = Epi::PERM ? ((R & ~31) + perm32(R & 31)) : R;
;         voffA[i] = (unsigned)(R * lda + C) * 2u; voffB[i] = (unsigned)(Rb * K + C) * 2u; }
;     const size_t kstep = (size_t)(BK * 2);
;     const size_t hstepA = (size_t)HALF * lda * 2, hstep = (size_t)HALF * K * 2;
;     const size_t tstepA = 2 * hstepA, tstep = 2 * hstep;
;     constexpr bool SPLIT = Epi::SPLIT;
;     const int ksp = nt >> 1;
;     const unsigned ldsw = (unsigned)wid * 1024u;
;     const int aoff = lds_byte(wr * 64 + fr, fq * 8), boff = lds_byte(wc * 32 + fr, fq * 8);
;     ...
;     PG8_STAGE(PG8_SB(0, 0), cB, voffB); PG8_STAGE(PG8_SA(0, 0), cA, voffA); PG8_STAGE(PG8_SB(0, 1), cB + hstep, voffB); PG8_STAGE(PG8_SA(0, 1), cA + hstepA, voffA);
;     if (wr == 1) PG8_BAR;
;     PG8_WAIT_V(4); PG8_BAR;
;     PG8_STAGE(PG8_SB(1, 0), cB + kstep, voffB); PG8_STAGE(PG8_SA(1, 0), cA + kstep, voffA); PG8_STAGE(PG8_SB(1, 1), cB + hstep + kstep, voffB);
;     PG8_WAIT_V(6); PG8_BAR;
.LBB0_54:
	v_and_b32_e32 v16, 15, v15
	v_and_b32_e32 v17, 48, v15
	v_lshlrev_b32_e32 v15, 2, v15
	s_sext_i32_i8 s85, s4
	s_and_b32 s4, s8, 3
	s_lshl_b32 s8, s5, 13
	v_lshl_or_b32 v18, v16, 6, v17
	v_and_b32_e32 v15, 32, v15
	v_bitop3_b32 v19, v18, s8, v15 bitop3:0xde
	s_lshl_b32 s8, s4, 12
	v_bitop3_b32 v202, v18, s8, v15 bitop3:0xde
	s_add_u32 s8, s64, 0x18000000
	s_addc_u32 s9, s65, 0
	s_add_u32 s10, s64, 0x1c000000
	s_addc_u32 s11, s65, 0
	s_add_i32 m0, s59, 0x18000
	v_lshl_add_u64 v[8:9], v[8:9], 0, s[48:49]
	global_load_lds_dwordx4 v[8:9], off
	v_lshl_add_u64 v[6:7], v[6:7], 0, s[48:49]
	s_add_i32 m0, s59, 0x1a000
	s_add_i32 s77, s59, 0x8000
	s_add_i32 s90, s59, 0xa000
	global_load_lds_dwordx4 v[6:7], off
	v_lshl_add_u64 v[4:5], v[4:5], 0, s[48:49]
	s_mov_b32 m0, s77
	s_add_u32 s22, s86, 0x80080
	global_load_lds_dwordx4 v[4:5], off
	v_lshl_add_u64 v[2:3], v[2:3], 0, s[48:49]
	s_mov_b32 m0, s90
	s_addc_u32 s23, s87, 0
	global_load_lds_dwordx4 v[2:3], off
	s_add_i32 m0, s59, 0x1c000
	v_lshl_add_u64 v[2:3], s[22:23], 0, v[184:185]
	global_load_lds_dwordx4 v[2:3], off
	v_lshl_add_u64 v[2:3], s[22:23], 0, v[180:181]
	s_add_i32 m0, s59, 0x1e000
	s_lshl_b32 s4, s4, 6
	global_load_lds_dwordx4 v[2:3], off
	s_waitcnt vmcnt(10)
	s_barrier
	v_lshlrev_b32_e32 v2, 11, v16
	v_lshl_or_b32 v2, s5, 17, v2
	v_or3_b32 v203, s4, v2, v17
	v_lshlrev_b32_e32 v2, 14, v0
	v_and_b32_e32 v2, 0xffff8000, v2
	v_lshl_add_u32 v2, v10, 11, v2
	v_and_b32_e32 v0, 1, v0
	v_lshl_or_b32 v0, v0, 6, v2
	v_lshl_add_u32 v188, v11, 1, v0
	v_lshlrev_b32_e32 v0, 14, v13
	v_and_b32_e32 v0, 0xffff8000, v0
	s_waitcnt vmcnt(6)
	v_lshl_add_u32 v0, v12, 11, v0
	v_and_b32_e32 v2, 1, v13
	v_lshl_or_b32 v0, v2, 6, v0
	v_mov_b32_e32 v189, v1
	v_lshl_add_u32 v190, v14, 1, v0
	v_mov_b32_e32 v191, v1
	s_mov_b32 s91, 0
	v_add_u32_e32 v204, 0, v19
	s_barrier
	s_branch .LBB0_56

; #define PG8_STAGE(bufoff, gbase, voff) do { _Pragma("unroll") for (int _i = 0; _i < 2; ++_i) \
;         __builtin_amdgcn_global_load_lds((const unsigned*)((const char*)(gbase) + (voff)[_i]), (PG8_LAS unsigned*)(lds + (bufoff) + ldsw + _i * 8192), 16, 0, 0); } while (0)
; #define PG8_WAIT_V(n) asm volatile("s_waitcnt vmcnt(" #n ")" ::: "memory")
; #define PG8_BAR __builtin_amdgcn_s_barrier()
; template <class Epi, class Sched>
; __device__ __forceinline__ void gemm_phase(PG8_LAS unsigned char* lds, const Gemm g, const Sched& S, const Epi& E, int wv) {
;     ...
;     for (int i = 0; i < 2; ++i) { int R, C; stage_rc(tid * 16 + i * 8192, R, C); const int Rb = Epi::PERM ? ((R & ~31) + perm32(R & 31)) : R;
;         voffA[i] = (unsigned)(R * lda + C) * 2u; voffB[i] = (unsigned)(Rb * K + C) * 2u; }
;     const size_t kstep = (size_t)(BK * 2);
;     const size_t hstepA = (size_t)HALF * lda * 2, hstep = (size_t)HALF * K * 2;
;     const size_t tstepA = 2 * hstepA, tstep = 2 * hstep;
;     constexpr bool SPLIT = Epi::SPLIT;
;     const int ksp = nt >> 1;
;     const unsigned ldsw = (unsigned)wid * 1024u;
;     const int aoff = lds_byte(wr * 64 + fr, fq * 8), boff = lds_byte(wc * 32 + fr, fq * 8);
;     ...
;     PG8_STAGE(PG8_SB(0, 0), cB, voffB); PG8_STAGE(PG8_SA(0, 0), cA, voffA); PG8_STAGE(PG8_SB(0, 1), cB + hstep, voffB); PG8_STAGE(PG8_SA(0, 1), cA + hstepA, voffA);
;     if (wr == 1) PG8_BAR;
;     PG8_WAIT_V(4); PG8_BAR;
;     PG8_STAGE(PG8_SB(1, 0), cB + kstep, voffB); PG8_STAGE(PG8_SA(1, 0), cA + kstep, voffA); PG8_STAGE(PG8_SB(1, 1), cB + hstep + kstep, voffB);
;     PG8_WAIT_V(6); PG8_BAR;
.LBB0_403:
	s_waitcnt lgkmcnt(0)
	s_add_u32 s16, s4, s90
	s_addc_u32 s17, s5, s77
	s_and_b32 s6, s6, 3
	s_add_i32 m0, s25, 0x18000
	v_lshl_add_u64 v[8:9], v[8:9], 0, s[48:49]
	s_lshl_b32 s8, s7, 13
	s_lshl_b32 s9, s6, 5
	s_lshl_b32 s10, s6, 12
	global_load_lds_dwordx4 v[8:9], off
	v_lshl_add_u64 v[6:7], v[6:7], 0, s[48:49]
	s_add_i32 m0, s25, 0x1a000
	s_add_i32 s94, s25, 0x8000
	s_add_i32 s95, s25, 0xa000
	global_load_lds_dwordx4 v[6:7], off
	v_lshl_add_u64 v[4:5], v[4:5], 0, s[48:49]
	s_mov_b32 m0, s94
	s_add_u32 s4, s84, 0x40080
	global_load_lds_dwordx4 v[4:5], off
	v_lshl_add_u64 v[2:3], v[2:3], 0, s[48:49]
	s_mov_b32 m0, s95
	s_addc_u32 s5, s85, 0
	global_load_lds_dwordx4 v[2:3], off
	s_add_i32 m0, s25, 0x1c000
	v_lshl_add_u64 v[2:3], s[4:5], 0, v[132:133]
	global_load_lds_dwordx4 v[2:3], off
	v_lshl_add_u64 v[2:3], s[4:5], 0, v[136:137]
	s_add_i32 m0, s25, 0x1e000
	v_bfe_u32 v4, v10, 4, 2
	global_load_lds_dwordx4 v[2:3], off
	s_waitcnt vmcnt(10)
	s_barrier
	v_and_b32_e32 v3, 15, v10
	v_lshlrev_b32_e32 v5, 4, v4
	v_lshl_or_b32 v158, s7, 6, v3
	v_lshl_or_b32 v3, v3, 6, v5
	v_lshlrev_b32_e32 v5, 2, v10
	v_and_b32_e32 v5, 32, v5
	v_bitop3_b32 v6, v3, s8, v5 bitop3:0xde
	v_bitop3_b32 v159, v3, s10, v5 bitop3:0xde
	s_add_i32 s7, 0, 0x20000
	v_lshlrev_b32_e32 v3, 5, v158
	v_add_u32_e32 v161, s7, v3
	s_lshl_b32 s6, s6, 2
	v_lshlrev_b32_e32 v2, 3, v4
	v_cmp_eq_u32_e64 s[4:5], 0, v4
	v_add_u32_e32 v162, s6, v161
	s_add_i32 s6, s7, s6
	v_or_b32_e32 v4, 0x200, v3
	v_or_b32_e32 v5, 0x400, v3
	v_or_b32_e32 v7, 0x600, v3
	v_add_u32_e32 v8, 0x1000, v3
	v_add_u32_e32 v9, 0x1200, v3
	v_add_u32_e32 v10, 0x1400, v3
	v_add_u32_e32 v3, 0x1600, v3
	v_add_u32_e32 v169, s6, v3
	v_add_u32_e32 v176, s7, v3
	v_lshlrev_b32_e32 v3, 14, v13
	v_and_b32_e32 v3, 0xffff8000, v3
	v_add_u32_e32 v163, s6, v4
	v_add_u32_e32 v170, s7, v4
	v_lshl_add_u32 v3, v14, 11, v3
	v_and_b32_e32 v4, 1, v13
	v_lshl_or_b32 v3, v4, 6, v3
	v_lshl_add_u32 v138, v15, 1, v3
	v_lshlrev_b32_e32 v3, 14, v0
	v_and_b32_e32 v3, 0xffff8000, v3
	s_waitcnt vmcnt(6)
	v_lshl_add_u32 v3, v11, 11, v3
	v_and_b32_e32 v0, 1, v0
	v_lshl_or_b32 v0, v0, 6, v3
	s_mov_b32 s96, 0
	v_or_b32_e32 v160, s9, v2
	v_add_u32_e32 v164, s6, v5
	v_add_u32_e32 v165, s6, v7
	v_add_u32_e32 v166, s6, v8
	v_add_u32_e32 v167, s6, v9
	v_add_u32_e32 v168, s6, v10
	v_add_u32_e32 v171, s7, v5
	v_add_u32_e32 v172, s7, v7
	v_add_u32_e32 v173, s7, v8
	v_add_u32_e32 v174, s7, v9
	v_add_u32_e32 v175, s7, v10
	v_mov_b32_e32 v139, v1
	v_lshl_add_u32 v140, v12, 1, v0
	v_mov_b32_e32 v141, v1
	v_add_u32_e32 v177, 0, v6
	s_lshl_b32 s97, s9, 2
	v_lshlrev_b32_e32 v178, 2, v2
	s_barrier
	s_branch .LBB0_406

; #define PG8_STAGE(bufoff, gbase, voff) do { _Pragma("unroll") for (int _i = 0; _i < 2; ++_i) \
;         __builtin_amdgcn_global_load_lds((const unsigned*)((const char*)(gbase) + (voff)[_i]), (PG8_LAS unsigned*)(lds + (bufoff) + ldsw + _i * 8192), 16, 0, 0); } while (0)
; #define PG8_WAIT_V(n) asm volatile("s_waitcnt vmcnt(" #n ")" ::: "memory")
; #define PG8_BAR __builtin_amdgcn_s_barrier()
; template <class Epi, class Sched>
; __device__ __forceinline__ void gemm_phase(PG8_LAS unsigned char* lds, const Gemm g, const Sched& S, const Epi& E, int wv) {
;     ...
;     for (int i = 0; i < 2; ++i) { int R, C; stage_rc(tid * 16 + i * 8192, R, C); const int Rb = Epi::PERM ? ((R & ~31) + perm32(R & 31)) : R;
;         voffA[i] = (unsigned)(R * lda + C) * 2u; voffB[i] = (unsigned)(Rb * K + C) * 2u; }
;     const size_t kstep = (size_t)(BK * 2);
;     const size_t hstepA = (size_t)HALF * lda * 2, hstep = (size_t)HALF * K * 2;
;     const size_t tstepA = 2 * hstepA, tstep = 2 * hstep;
;     constexpr bool SPLIT = Epi::SPLIT;
;     const int ksp = nt >> 1;
;     const unsigned ldsw = (unsigned)wid * 1024u;
;     const int aoff = lds_byte(wr * 64 + fr, fq * 8), boff = lds_byte(wc * 32 + fr, fq * 8);
;     ...
;     PG8_STAGE(PG8_SB(0, 0), cB, voffB); PG8_STAGE(PG8_SA(0, 0), cA, voffA); PG8_STAGE(PG8_SB(0, 1), cB + hstep, voffB); PG8_STAGE(PG8_SA(0, 1), cA + hstepA, voffA);
;     if (wr == 1) PG8_BAR;
;     PG8_WAIT_V(4); PG8_BAR;
;     PG8_STAGE(PG8_SB(1, 0), cB + kstep, voffB); PG8_STAGE(PG8_SA(1, 0), cA + kstep, voffA); PG8_STAGE(PG8_SB(1, 1), cB + hstep + kstep, voffB);
;     PG8_WAIT_V(6); PG8_BAR;
.LBB0_499:
	v_bfe_u32 v18, v0, 4, 2
	s_lshl_b32 s4, s4, 5
	s_sext_i32_i8 s80, s6
	v_and_b32_e32 v188, 15, v0
	v_lshlrev_b32_e32 v19, 4, v18
	v_lshlrev_b32_e32 v20, 2, v0
	s_and_b32 s6, s4, 0x60
	s_add_i32 m0, s46, 0x18000
	v_lshl_add_u64 v[8:9], v[8:9], 0, s[48:49]
	s_lshl_b32 s61, s5, 6
	v_lshl_or_b32 v19, v188, 6, v19
	s_lshl_b32 s5, s5, 13
	v_and_b32_e32 v20, 32, v20
	s_lshl_b32 s4, s6, 7
	global_load_lds_dwordx4 v[8:9], off
	v_lshl_add_u64 v[6:7], v[6:7], 0, s[48:49]
	s_add_i32 m0, s46, 0x1a000
	s_add_i32 s74, s46, 0x8000
	s_add_i32 s75, s46, 0xa000
	v_bitop3_b32 v189, v19, s4, v20 bitop3:0xde
	global_load_lds_dwordx4 v[6:7], off
	v_lshl_add_u64 v[4:5], v[4:5], 0, s[48:49]
	s_mov_b32 m0, s74
	s_add_u32 s4, s18, 0xb0080
	v_bitop3_b32 v21, v19, s5, v20 bitop3:0xde
	global_load_lds_dwordx4 v[4:5], off
	v_lshl_add_u64 v[2:3], v[2:3], 0, s[48:49]
	s_mov_b32 m0, s75
	s_addc_u32 s5, s19, 0
	global_load_lds_dwordx4 v[2:3], off
	s_add_i32 m0, s46, 0x1c000
	v_lshl_add_u64 v[2:3], s[4:5], 0, v[180:181]
	global_load_lds_dwordx4 v[2:3], off
	v_lshl_add_u64 v[2:3], s[4:5], 0, v[178:179]
	s_add_i32 m0, s46, 0x1e000
	s_movk_i32 s9, 0xb00
	global_load_lds_dwordx4 v[2:3], off
	s_waitcnt vmcnt(10)
	s_barrier
	v_and_b32_e32 v190, 7, v0
	v_lshrrev_b32_e32 v2, 1, v10
	v_mul_lo_u32 v0, v11, s9
	s_mov_b32 s8, 0xb000
	v_lshl_or_b32 v192, v18, 2, s6
	v_mad_u64_u32 v[2:3], s[6:7], v2, s8, v[0:1]
	v_or_b32_e32 v0, v2, v12
	v_add_lshl_u32 v0, v0, v13, 1
	s_mov_b64 s[10:11], 0xb0080
	v_lshl_add_u64 v[182:183], v[0:1], 0, s[10:11]
	v_lshrrev_b32_e32 v2, 1, v15
	v_mul_lo_u32 v0, v14, s9
	v_mad_u64_u32 v[2:3], s[6:7], v2, s8, v[0:1]
	s_waitcnt vmcnt(6)
	v_or_b32_e32 v0, v2, v16
	v_cmp_gt_u32_e64 s[4:5], 8, v188
	v_add_lshl_u32 v0, v0, v17, 1
	s_mov_b32 s76, 0
	v_cndmask_b32_e64 v191, 64, 0, s[4:5]
	v_lshl_add_u64 v[184:185], v[0:1], 0, s[10:11]
	v_add_u32_e32 v193, 0, v21
	s_barrier

; #define PG8_STAGE(bufoff, gbase, voff) do { _Pragma("unroll") for (int _i = 0; _i < 2; ++_i) \
;         __builtin_amdgcn_global_load_lds((const unsigned*)((const char*)(gbase) + (voff)[_i]), (PG8_LAS unsigned*)(lds + (bufoff) + ldsw + _i * 8192), 16, 0, 0); } while (0)
; #define PG8_WAIT_V(n) asm volatile("s_waitcnt vmcnt(" #n ")" ::: "memory")
; #define PG8_BAR __builtin_amdgcn_s_barrier()
; template <class Epi, class Sched>
; __device__ __forceinline__ void gemm_phase(PG8_LAS unsigned char* lds, const Gemm g, const Sched& S, const Epi& E, int wv) {
;     ...
;     for (int i = 0; i < 2; ++i) { int R, C; stage_rc(tid * 16 + i * 8192, R, C); const int Rb = Epi::PERM ? ((R & ~31) + perm32(R & 31)) : R;
;         voffA[i] = (unsigned)(R * lda + C) * 2u; voffB[i] = (unsigned)(Rb * K + C) * 2u; }
;     const size_t kstep = (size_t)(BK * 2);
;     const size_t hstepA = (size_t)HALF * lda * 2, hstep = (size_t)HALF * K * 2;
;     const size_t tstepA = 2 * hstepA, tstep = 2 * hstep;
;     constexpr bool SPLIT = Epi::SPLIT;
;     const int ksp = nt >> 1;
;     const unsigned ldsw = (unsigned)wid * 1024u;
;     const int aoff = lds_byte(wr * 64 + fr, fq * 8), boff = lds_byte(wc * 32 + fr, fq * 8);
;     ...
;     PG8_STAGE(PG8_SB(0, 0), cB, voffB); PG8_STAGE(PG8_SA(0, 0), cA, voffA); PG8_STAGE(PG8_SB(0, 1), cB + hstep, voffB); PG8_STAGE(PG8_SA(0, 1), cA + hstepA, voffA);
;     if (wr == 1) PG8_BAR;
;     PG8_WAIT_V(4); PG8_BAR;
;     PG8_STAGE(PG8_SB(1, 0), cB + kstep, voffB); PG8_STAGE(PG8_SA(1, 0), cA + kstep, voffA); PG8_STAGE(PG8_SB(1, 1), cB + hstep + kstep, voffB);
;     PG8_WAIT_V(6); PG8_BAR;
.LBB0_521:
	v_mov_b32_e32 v137, v1
	v_lshl_add_u64 v[8:9], s[18:19], 0, v[136:137]
	v_mov_b32_e32 v133, v1
	s_lshl_b32 s6, s6, 5
	v_lshl_add_u64 v[10:11], s[18:19], 0, v[132:133]
	v_mov_b32_e32 v139, v1
	s_and_b32 s9, s6, 0x60
	s_add_i32 m0, s11, 0x18000
	v_lshl_add_u64 v[8:9], v[8:9], 0, s[48:49]
	v_lshl_add_u64 v[12:13], s[20:21], 0, v[138:139]
	v_mov_b32_e32 v135, v1
	s_lshl_b32 s8, s5, 13
	s_lshl_b32 s12, s9, 7
	global_load_lds_dwordx4 v[8:9], off
	v_lshl_add_u64 v[8:9], v[10:11], 0, s[48:49]
	s_add_i32 m0, s11, 0x1a000
	s_add_i32 s60, s11, 0x8000
	s_add_i32 s61, s11, 0xa000
	v_lshl_add_u64 v[14:15], s[20:21], 0, v[134:135]
	global_load_lds_dwordx4 v[8:9], off
	v_lshl_add_u64 v[8:9], v[12:13], 0, s[48:49]
	s_mov_b32 m0, s60
	s_add_u32 s6, s18, 0x40080
	global_load_lds_dwordx4 v[8:9], off
	v_lshl_add_u64 v[8:9], v[14:15], 0, s[48:49]
	s_mov_b32 m0, s61
	s_addc_u32 s7, s19, 0
	global_load_lds_dwordx4 v[8:9], off
	s_add_i32 m0, s11, 0x1c000
	v_lshl_add_u64 v[8:9], s[6:7], 0, v[136:137]
	global_load_lds_dwordx4 v[8:9], off
	v_lshl_add_u64 v[8:9], s[6:7], 0, v[132:133]
	s_add_i32 m0, s11, 0x1e000
	s_sext_i32_i16 s75, s4
	global_load_lds_dwordx4 v[8:9], off
	s_waitcnt vmcnt(10)
	s_barrier
	v_lshrrev_b32_e32 v9, 1, v0
	v_and_b32_e32 v9, 24, v9
	v_and_b32_e32 v8, 15, v0
	v_lshlrev_b32_e32 v10, 1, v9
	v_lshlrev_b32_e32 v0, 2, v0
	v_lshl_or_b32 v146, s5, 6, v8
	v_lshl_or_b32 v8, v8, 6, v10
	v_and_b32_e32 v0, 32, v0
	v_bitop3_b32 v10, v8, s8, v0 bitop3:0xde
	v_bitop3_b32 v147, v8, s12, v0 bitop3:0xde
	v_lshlrev_b32_e32 v0, 14, v2
	v_and_b32_e32 v0, 0xffff8000, v0
	v_lshl_add_u32 v0, v3, 11, v0
	v_and_b32_e32 v2, 1, v2
	v_lshl_or_b32 v0, v2, 6, v0
	v_lshl_add_u32 v220, v4, 1, v0
	v_lshlrev_b32_e32 v0, 14, v6
	v_and_b32_e32 v0, 0xffff8000, v0
	s_waitcnt vmcnt(6)
	v_lshl_add_u32 v0, v5, 11, v0
	v_and_b32_e32 v2, 1, v6
	v_lshl_or_b32 v0, v2, 6, v0
	v_or_b32_e32 v148, s9, v9
	v_mov_b32_e32 v221, v1
	v_lshl_add_u32 v222, v7, 1, v0
	v_mov_b32_e32 v223, v1
	s_mov_b32 s74, 0
	s_mov_b64 s[22:23], 0
	v_add_u32_e32 v149, 0, v10
	s_barrier
	s_waitcnt vmcnt(0)
